# adds 64-bit accumulator clears and a 4-deep p-to-bf16 load pipeline on top of the chained MFMA order
# baseline (speedup 1.0000x reference)
.LBB0_59:
	s_ashr_i32 s13, s12, 31
	s_lshl_b64 s[14:15], s[12:13], 20
	s_add_u32 s14, s26, s14
	s_addc_u32 s15, s27, s15
	s_and_b64 s[16:17], s[4:5], exec
	s_cselect_b32 s13, s15, s7
	s_cselect_b32 s19, s14, s6
	s_ashr_i32 s11, s10, 31
	s_lshl_b64 s[16:17], s[10:11], 20
	s_add_u32 s16, s31, s16
	s_addc_u32 s17, s37, s17
	s_and_b64 s[44:45], s[4:5], exec
	s_cselect_b32 s11, s17, s43
	s_cselect_b32 s41, s16, s42
	s_add_u32 s6, s6, 0x80080
	s_addc_u32 s7, s7, 0
	s_add_u32 s46, s42, 0x100
	v_mov_b32_e32 v32, 0
	s_mov_b64 s[8:9], s[70:71]
	s_mov_b32 s70, s69
	s_addc_u32 s47, s43, 0
	s_mov_b32 s48, -2
	v_mov_b32_e32 v33, 0
	v_mov_b64_e32 v[34:35], 0
	v_mov_b64_e32 v[36:37], 0
	v_mov_b64_e32 v[38:39], 0
	v_mov_b64_e32 v[48:49], 0
	v_mov_b64_e32 v[50:51], 0
	v_mov_b64_e32 v[52:53], 0
	v_mov_b64_e32 v[54:55], 0
	v_mov_b64_e32 v[64:65], 0
	v_mov_b64_e32 v[66:67], 0
	v_mov_b64_e32 v[68:69], 0
	v_mov_b64_e32 v[70:71], 0
	v_mov_b64_e32 v[80:81], 0
	v_mov_b64_e32 v[82:83], 0
	v_mov_b64_e32 v[84:85], 0
	v_mov_b64_e32 v[86:87], 0
	v_mov_b64_e32 v[40:41], 0
	v_mov_b64_e32 v[42:43], 0
	v_mov_b64_e32 v[44:45], 0
	v_mov_b64_e32 v[46:47], 0
	v_mov_b64_e32 v[56:57], 0
	v_mov_b64_e32 v[58:59], 0
	v_mov_b64_e32 v[60:61], 0
	v_mov_b64_e32 v[62:63], 0
	v_mov_b64_e32 v[72:73], 0
	v_mov_b64_e32 v[74:75], 0
	v_mov_b64_e32 v[76:77], 0
	v_mov_b64_e32 v[78:79], 0
	v_mov_b64_e32 v[88:89], 0
	v_mov_b64_e32 v[90:91], 0
	v_mov_b64_e32 v[92:93], 0
	v_mov_b64_e32 v[94:95], 0
	v_mov_b64_e32 v[96:97], 0
	v_mov_b64_e32 v[98:99], 0
	v_mov_b64_e32 v[100:101], 0
	v_mov_b64_e32 v[102:103], 0
	v_mov_b64_e32 v[112:113], 0
	v_mov_b64_e32 v[114:115], 0
	v_mov_b64_e32 v[116:117], 0
	v_mov_b64_e32 v[118:119], 0
	v_mov_b64_e32 v[128:129], 0
	v_mov_b64_e32 v[130:131], 0
	v_mov_b64_e32 v[132:133], 0
	v_mov_b64_e32 v[134:135], 0
	v_mov_b64_e32 v[144:145], 0
	v_mov_b64_e32 v[146:147], 0
	v_mov_b64_e32 v[148:149], 0
	v_mov_b64_e32 v[150:151], 0
	v_mov_b64_e32 v[104:105], 0
	v_mov_b64_e32 v[106:107], 0
	v_mov_b64_e32 v[108:109], 0
	v_mov_b64_e32 v[110:111], 0
	v_mov_b64_e32 v[120:121], 0
	v_mov_b64_e32 v[122:123], 0
	v_mov_b64_e32 v[124:125], 0
	v_mov_b64_e32 v[126:127], 0
	v_mov_b64_e32 v[136:137], 0
	v_mov_b64_e32 v[138:139], 0
	v_mov_b64_e32 v[140:141], 0
	v_mov_b64_e32 v[142:143], 0
	v_mov_b64_e32 v[152:153], 0
	v_mov_b64_e32 v[154:155], 0
	v_mov_b64_e32 v[156:157], 0
	v_mov_b64_e32 v[158:159], 0

.LBB0_169:
	s_ashr_i32 s11, s10, 31
	s_lshl_b64 s[12:13], s[10:11], 20
	s_add_u32 s12, s38, s12
	s_addc_u32 s13, s39, s13
	s_and_b64 s[14:15], s[4:5], exec
	s_cselect_b32 s11, s13, s41
	s_cselect_b32 s17, s12, s40
	s_ashr_i32 s7, s6, 31
	s_lshl_b64 s[14:15], s[6:7], 20
	s_add_u32 s14, s31, s14
	s_addc_u32 s15, s37, s15
	s_and_b64 s[44:45], s[4:5], exec
	s_cselect_b32 s7, s15, s43
	s_cselect_b32 s19, s14, s42
	s_add_u32 s40, s40, 0x80080
	s_addc_u32 s41, s41, 0
	s_add_u32 s57, s42, 0x100
	v_mov_b32_e32 v4, 0
	s_addc_u32 s63, s43, 0
	s_mov_b32 s64, -2
	s_waitcnt lgkmcnt(0)
	v_mov_b32_e32 v5, 0
	v_mov_b64_e32 v[6:7], 0
	v_mov_b64_e32 v[8:9], 0
	v_mov_b64_e32 v[10:11], 0
	v_mov_b64_e32 v[20:21], 0
	v_mov_b64_e32 v[22:23], 0
	v_mov_b64_e32 v[24:25], 0
	v_mov_b64_e32 v[26:27], 0
	v_mov_b64_e32 v[36:37], 0
	v_mov_b64_e32 v[38:39], 0
	v_mov_b64_e32 v[40:41], 0
	v_mov_b64_e32 v[42:43], 0
	v_mov_b64_e32 v[52:53], 0
	v_mov_b64_e32 v[54:55], 0
	v_mov_b64_e32 v[56:57], 0
	v_mov_b64_e32 v[58:59], 0
	v_mov_b64_e32 v[0:1], 0
	v_mov_b64_e32 v[2:3], 0
	v_mov_b64_e32 v[12:13], 0
	v_mov_b64_e32 v[14:15], 0
	v_mov_b64_e32 v[16:17], 0
	v_mov_b64_e32 v[18:19], 0
	v_mov_b64_e32 v[28:29], 0
	v_mov_b64_e32 v[30:31], 0
	v_mov_b64_e32 v[32:33], 0
	v_mov_b64_e32 v[34:35], 0
	v_mov_b64_e32 v[44:45], 0
	v_mov_b64_e32 v[46:47], 0
	v_mov_b64_e32 v[48:49], 0
	v_mov_b64_e32 v[50:51], 0
	v_mov_b64_e32 v[60:61], 0
	v_mov_b64_e32 v[62:63], 0
	v_mov_b64_e32 v[68:69], 0
	v_mov_b64_e32 v[70:71], 0
	v_mov_b64_e32 v[72:73], 0
	v_mov_b64_e32 v[74:75], 0
	v_mov_b64_e32 v[84:85], 0
	v_mov_b64_e32 v[86:87], 0
	v_mov_b64_e32 v[88:89], 0
	v_mov_b64_e32 v[90:91], 0
	v_mov_b64_e32 v[100:101], 0
	v_mov_b64_e32 v[102:103], 0
	v_mov_b64_e32 v[104:105], 0
	v_mov_b64_e32 v[106:107], 0
	v_mov_b64_e32 v[120:121], 0
	v_mov_b64_e32 v[122:123], 0
	v_mov_b64_e32 v[124:125], 0
	v_mov_b64_e32 v[126:127], 0
	v_mov_b64_e32 v[64:65], 0
	v_mov_b64_e32 v[66:67], 0
	v_mov_b64_e32 v[76:77], 0
	v_mov_b64_e32 v[78:79], 0
	v_mov_b64_e32 v[80:81], 0
	v_mov_b64_e32 v[82:83], 0
	v_mov_b64_e32 v[92:93], 0
	v_mov_b64_e32 v[94:95], 0
	v_mov_b64_e32 v[96:97], 0
	v_mov_b64_e32 v[98:99], 0
	v_mov_b64_e32 v[108:109], 0
	v_mov_b64_e32 v[110:111], 0
	v_mov_b64_e32 v[112:113], 0
	v_mov_b64_e32 v[114:115], 0
	v_mov_b64_e32 v[116:117], 0
	v_mov_b64_e32 v[118:119], 0

.LBB0_243:
	s_ashr_i32 s11, s10, 31
	s_lshl_b64 s[12:13], s[10:11], 20
	s_add_u32 s12, s26, s12
	s_addc_u32 s13, s27, s13
	s_and_b64 s[14:15], s[4:5], exec
	s_cselect_b32 s11, s13, s7
	s_cselect_b32 s47, s12, s6
	s_ashr_i32 s9, s8, 31
	s_lshl_b64 s[14:15], s[8:9], 20
	s_add_u32 s14, s37, s14
	s_addc_u32 s15, s38, s15
	s_and_b64 s[30:31], s[4:5], exec
	s_cselect_b32 s9, s15, s19
	s_cselect_b32 s48, s14, s18
	s_add_u32 s6, s6, 0x80080
	s_addc_u32 s7, s7, 0
	s_add_u32 s49, s18, 0x100
	v_mov_b32_e32 v32, 0
	s_addc_u32 s50, s19, 0
	s_mov_b32 s51, -2
	v_mov_b32_e32 v33, 0
	v_mov_b64_e32 v[34:35], 0
	v_mov_b64_e32 v[36:37], 0
	v_mov_b64_e32 v[38:39], 0
	v_mov_b64_e32 v[40:41], 0
	v_mov_b64_e32 v[42:43], 0
	v_mov_b64_e32 v[48:49], 0
	v_mov_b64_e32 v[50:51], 0
	v_mov_b64_e32 v[56:57], 0
	v_mov_b64_e32 v[58:59], 0
	v_mov_b64_e32 v[64:65], 0
	v_mov_b64_e32 v[66:67], 0
	v_mov_b64_e32 v[72:73], 0
	v_mov_b64_e32 v[74:75], 0
	v_mov_b64_e32 v[80:81], 0
	v_mov_b64_e32 v[82:83], 0
	v_mov_b64_e32 v[44:45], 0
	v_mov_b64_e32 v[46:47], 0
	v_mov_b64_e32 v[52:53], 0
	v_mov_b64_e32 v[54:55], 0
	v_mov_b64_e32 v[60:61], 0
	v_mov_b64_e32 v[62:63], 0
	v_mov_b64_e32 v[68:69], 0
	v_mov_b64_e32 v[70:71], 0
	v_mov_b64_e32 v[76:77], 0
	v_mov_b64_e32 v[78:79], 0
	v_mov_b64_e32 v[84:85], 0
	v_mov_b64_e32 v[86:87], 0
	v_mov_b64_e32 v[88:89], 0
	v_mov_b64_e32 v[90:91], 0
	v_mov_b64_e32 v[92:93], 0
	v_mov_b64_e32 v[94:95], 0
	v_mov_b64_e32 v[96:97], 0
	v_mov_b64_e32 v[98:99], 0
	v_mov_b64_e32 v[100:101], 0
	v_mov_b64_e32 v[102:103], 0
	v_mov_b64_e32 v[104:105], 0
	v_mov_b64_e32 v[106:107], 0
	v_mov_b64_e32 v[112:113], 0
	v_mov_b64_e32 v[114:115], 0
	v_mov_b64_e32 v[120:121], 0
	v_mov_b64_e32 v[122:123], 0
	v_mov_b64_e32 v[128:129], 0
	v_mov_b64_e32 v[130:131], 0
	v_mov_b64_e32 v[136:137], 0
	v_mov_b64_e32 v[138:139], 0
	v_mov_b64_e32 v[144:145], 0
	v_mov_b64_e32 v[146:147], 0
	v_mov_b64_e32 v[108:109], 0
	v_mov_b64_e32 v[110:111], 0
	v_mov_b64_e32 v[116:117], 0
	v_mov_b64_e32 v[118:119], 0
	v_mov_b64_e32 v[124:125], 0
	v_mov_b64_e32 v[126:127], 0
	v_mov_b64_e32 v[132:133], 0
	v_mov_b64_e32 v[134:135], 0
	v_mov_b64_e32 v[140:141], 0
	v_mov_b64_e32 v[142:143], 0
	v_mov_b64_e32 v[148:149], 0
	v_mov_b64_e32 v[150:151], 0
	v_mov_b64_e32 v[152:153], 0
	v_mov_b64_e32 v[154:155], 0
	v_mov_b64_e32 v[156:157], 0
	v_mov_b64_e32 v[158:159], 0

.LBB0_277:
	s_add_u32 s19, s12, 0x100
	v_mov_b32_e32 v0, 0
	s_addc_u32 s30, s13, 0
	s_mov_b32 s31, -2
	s_waitcnt lgkmcnt(0)
	v_mov_b32_e32 v1, 0
	v_mov_b64_e32 v[2:3], 0
	v_mov_b64_e32 v[4:5], 0
	v_mov_b64_e32 v[6:7], 0
	v_mov_b64_e32 v[16:17], 0
	v_mov_b64_e32 v[18:19], 0
	v_mov_b64_e32 v[20:21], 0
	v_mov_b64_e32 v[22:23], 0
	v_mov_b64_e32 v[32:33], 0
	v_mov_b64_e32 v[34:35], 0
	v_mov_b64_e32 v[36:37], 0
	v_mov_b64_e32 v[38:39], 0
	v_mov_b64_e32 v[48:49], 0
	v_mov_b64_e32 v[50:51], 0
	v_mov_b64_e32 v[52:53], 0
	v_mov_b64_e32 v[54:55], 0
	v_mov_b64_e32 v[8:9], 0
	v_mov_b64_e32 v[10:11], 0
	v_mov_b64_e32 v[12:13], 0
	v_mov_b64_e32 v[14:15], 0
	v_mov_b64_e32 v[24:25], 0
	v_mov_b64_e32 v[26:27], 0
	v_mov_b64_e32 v[28:29], 0
	v_mov_b64_e32 v[30:31], 0
	v_mov_b64_e32 v[40:41], 0
	v_mov_b64_e32 v[42:43], 0
	v_mov_b64_e32 v[44:45], 0
	v_mov_b64_e32 v[46:47], 0
	v_mov_b64_e32 v[56:57], 0
	v_mov_b64_e32 v[58:59], 0
	v_mov_b64_e32 v[60:61], 0
	v_mov_b64_e32 v[62:63], 0
	v_mov_b64_e32 v[64:65], 0
	v_mov_b64_e32 v[66:67], 0
	v_mov_b64_e32 v[68:69], 0
	v_mov_b64_e32 v[70:71], 0
	v_mov_b64_e32 v[80:81], 0
	v_mov_b64_e32 v[82:83], 0
	v_mov_b64_e32 v[84:85], 0
	v_mov_b64_e32 v[86:87], 0
	v_mov_b64_e32 v[96:97], 0
	v_mov_b64_e32 v[98:99], 0
	v_mov_b64_e32 v[100:101], 0
	v_mov_b64_e32 v[102:103], 0
	v_mov_b64_e32 v[112:113], 0
	v_mov_b64_e32 v[114:115], 0
	v_mov_b64_e32 v[116:117], 0
	v_mov_b64_e32 v[118:119], 0
	v_mov_b64_e32 v[72:73], 0
	v_mov_b64_e32 v[74:75], 0
	v_mov_b64_e32 v[76:77], 0
	v_mov_b64_e32 v[78:79], 0
	v_mov_b64_e32 v[88:89], 0
	v_mov_b64_e32 v[90:91], 0
	v_mov_b64_e32 v[92:93], 0
	v_mov_b64_e32 v[94:95], 0
	v_mov_b64_e32 v[104:105], 0
	v_mov_b64_e32 v[106:107], 0
	v_mov_b64_e32 v[108:109], 0
	v_mov_b64_e32 v[110:111], 0
	v_mov_b64_e32 v[120:121], 0
	v_mov_b64_e32 v[122:123], 0
	v_mov_b64_e32 v[124:125], 0
	v_mov_b64_e32 v[126:127], 0

.LBB0_408:
	s_ashr_i32 s11, s10, 31
	s_lshl_b64 s[12:13], s[10:11], 20
	s_add_u32 s12, s26, s12
	s_addc_u32 s13, s27, s13
	s_and_b64 s[14:15], s[4:5], exec
	s_cselect_b32 s11, s13, s7
	s_cselect_b32 s44, s12, s6
	s_ashr_i32 s9, s8, 31
	s_lshl_b64 s[14:15], s[8:9], 20
	s_add_u32 s14, s30, s14
	s_addc_u32 s15, s31, s15
	s_and_b64 s[22:23], s[4:5], exec
	s_cselect_b32 s9, s15, s19
	s_cselect_b32 s45, s14, s18
	s_add_u32 s6, s6, 0x80080
	s_addc_u32 s7, s7, 0
	s_add_u32 s46, s18, 0x100
	v_mov_b32_e32 v32, 0
	s_addc_u32 s47, s19, 0
	s_mov_b32 s48, -2
	v_mov_b32_e32 v33, 0
	v_mov_b64_e32 v[34:35], 0
	v_mov_b64_e32 v[36:37], 0
	v_mov_b64_e32 v[38:39], 0
	v_mov_b64_e32 v[48:49], 0
	v_mov_b64_e32 v[50:51], 0
	v_mov_b64_e32 v[52:53], 0
	v_mov_b64_e32 v[54:55], 0
	v_mov_b64_e32 v[64:65], 0
	v_mov_b64_e32 v[66:67], 0
	v_mov_b64_e32 v[68:69], 0
	v_mov_b64_e32 v[70:71], 0
	v_mov_b64_e32 v[80:81], 0
	v_mov_b64_e32 v[82:83], 0
	v_mov_b64_e32 v[84:85], 0
	v_mov_b64_e32 v[86:87], 0
	v_mov_b64_e32 v[40:41], 0
	v_mov_b64_e32 v[42:43], 0
	v_mov_b64_e32 v[44:45], 0
	v_mov_b64_e32 v[46:47], 0
	v_mov_b64_e32 v[56:57], 0
	v_mov_b64_e32 v[58:59], 0
	v_mov_b64_e32 v[60:61], 0
	v_mov_b64_e32 v[62:63], 0
	v_mov_b64_e32 v[72:73], 0
	v_mov_b64_e32 v[74:75], 0
	v_mov_b64_e32 v[76:77], 0
	v_mov_b64_e32 v[78:79], 0
	v_mov_b64_e32 v[88:89], 0
	v_mov_b64_e32 v[90:91], 0
	v_mov_b64_e32 v[92:93], 0
	v_mov_b64_e32 v[94:95], 0
	v_mov_b64_e32 v[96:97], 0
	v_mov_b64_e32 v[98:99], 0
	v_mov_b64_e32 v[100:101], 0
	v_mov_b64_e32 v[102:103], 0
	v_mov_b64_e32 v[112:113], 0
	v_mov_b64_e32 v[114:115], 0
	v_mov_b64_e32 v[116:117], 0
	v_mov_b64_e32 v[118:119], 0
	v_mov_b64_e32 v[128:129], 0
	v_mov_b64_e32 v[130:131], 0
	v_mov_b64_e32 v[132:133], 0
	v_mov_b64_e32 v[134:135], 0
	v_mov_b64_e32 v[144:145], 0
	v_mov_b64_e32 v[146:147], 0
	v_mov_b64_e32 v[148:149], 0
	v_mov_b64_e32 v[150:151], 0
	v_mov_b64_e32 v[104:105], 0
	v_mov_b64_e32 v[106:107], 0
	v_mov_b64_e32 v[108:109], 0
	v_mov_b64_e32 v[110:111], 0
	v_mov_b64_e32 v[120:121], 0
	v_mov_b64_e32 v[122:123], 0
	v_mov_b64_e32 v[124:125], 0
	v_mov_b64_e32 v[126:127], 0
	v_mov_b64_e32 v[136:137], 0
	v_mov_b64_e32 v[138:139], 0
	v_mov_b64_e32 v[140:141], 0
	v_mov_b64_e32 v[142:143], 0
	v_mov_b64_e32 v[152:153], 0
	v_mov_b64_e32 v[154:155], 0
	v_mov_b64_e32 v[156:157], 0
	v_mov_b64_e32 v[158:159], 0

.LBB0_442:
	s_add_u32 s19, s12, 0x100
	v_mov_b32_e32 v0, 0
	s_addc_u32 s22, s13, 0
	s_mov_b32 s23, -2
	s_waitcnt lgkmcnt(0)
	v_mov_b32_e32 v1, 0
	v_mov_b64_e32 v[2:3], 0
	v_mov_b64_e32 v[4:5], 0
	v_mov_b64_e32 v[6:7], 0
	v_mov_b64_e32 v[16:17], 0
	v_mov_b64_e32 v[18:19], 0
	v_mov_b64_e32 v[20:21], 0
	v_mov_b64_e32 v[22:23], 0
	v_mov_b64_e32 v[32:33], 0
	v_mov_b64_e32 v[34:35], 0
	v_mov_b64_e32 v[36:37], 0
	v_mov_b64_e32 v[38:39], 0
	v_mov_b64_e32 v[48:49], 0
	v_mov_b64_e32 v[50:51], 0
	v_mov_b64_e32 v[52:53], 0
	v_mov_b64_e32 v[54:55], 0
	v_mov_b64_e32 v[8:9], 0
	v_mov_b64_e32 v[10:11], 0
	v_mov_b64_e32 v[12:13], 0
	v_mov_b64_e32 v[14:15], 0
	v_mov_b64_e32 v[24:25], 0
	v_mov_b64_e32 v[26:27], 0
	v_mov_b64_e32 v[28:29], 0
	v_mov_b64_e32 v[30:31], 0
	v_mov_b64_e32 v[40:41], 0
	v_mov_b64_e32 v[42:43], 0
	v_mov_b64_e32 v[44:45], 0
	v_mov_b64_e32 v[46:47], 0
	v_mov_b64_e32 v[56:57], 0
	v_mov_b64_e32 v[58:59], 0
	v_mov_b64_e32 v[60:61], 0
	v_mov_b64_e32 v[62:63], 0
	v_mov_b64_e32 v[64:65], 0
	v_mov_b64_e32 v[66:67], 0
	v_mov_b64_e32 v[68:69], 0
	v_mov_b64_e32 v[70:71], 0
	v_mov_b64_e32 v[80:81], 0
	v_mov_b64_e32 v[82:83], 0
	v_mov_b64_e32 v[84:85], 0
	v_mov_b64_e32 v[86:87], 0
	v_mov_b64_e32 v[96:97], 0
	v_mov_b64_e32 v[98:99], 0
	v_mov_b64_e32 v[100:101], 0
	v_mov_b64_e32 v[102:103], 0
	v_mov_b64_e32 v[112:113], 0
	v_mov_b64_e32 v[114:115], 0
	v_mov_b64_e32 v[116:117], 0
	v_mov_b64_e32 v[118:119], 0
	v_mov_b64_e32 v[72:73], 0
	v_mov_b64_e32 v[74:75], 0
	v_mov_b64_e32 v[76:77], 0
	v_mov_b64_e32 v[78:79], 0
	v_mov_b64_e32 v[88:89], 0
	v_mov_b64_e32 v[90:91], 0
	v_mov_b64_e32 v[92:93], 0
	v_mov_b64_e32 v[94:95], 0
	v_mov_b64_e32 v[104:105], 0
	v_mov_b64_e32 v[106:107], 0
	v_mov_b64_e32 v[108:109], 0
	v_mov_b64_e32 v[110:111], 0
	v_mov_b64_e32 v[120:121], 0
	v_mov_b64_e32 v[122:123], 0
	v_mov_b64_e32 v[124:125], 0
	v_mov_b64_e32 v[126:127], 0

.LBB0_543:
	s_ashr_i32 s11, s10, 31
	s_lshl_b64 s[12:13], s[10:11], 20
	s_add_u32 s12, s0, s12
	s_addc_u32 s13, s1, s13
	s_and_b64 s[14:15], s[4:5], exec
	s_cselect_b32 s11, s13, s7
	s_cselect_b32 s38, s12, s6
	s_ashr_i32 s9, s8, 31
	s_lshl_b64 s[14:15], s[8:9], 20
	s_add_u32 s14, s26, s14
	s_addc_u32 s15, s27, s15
	s_and_b64 s[22:23], s[4:5], exec
	s_cselect_b32 s9, s15, s19
	s_cselect_b32 s39, s14, s18
	s_add_u32 s6, s6, 0x80080
	s_addc_u32 s7, s7, 0
	s_add_u32 s40, s18, 0x100
	v_mov_b32_e32 v32, 0
	s_addc_u32 s41, s19, 0
	s_mov_b32 s42, -2
	v_mov_b32_e32 v33, 0
	v_mov_b64_e32 v[34:35], 0
	v_mov_b64_e32 v[40:41], 0
	v_mov_b64_e32 v[42:43], 0
	v_mov_b64_e32 v[48:49], 0
	v_mov_b64_e32 v[50:51], 0
	v_mov_b64_e32 v[56:57], 0
	v_mov_b64_e32 v[58:59], 0
	v_mov_b64_e32 v[64:65], 0
	v_mov_b64_e32 v[66:67], 0
	v_mov_b64_e32 v[72:73], 0
	v_mov_b64_e32 v[74:75], 0
	v_mov_b64_e32 v[80:81], 0
	v_mov_b64_e32 v[82:83], 0
	v_mov_b64_e32 v[88:89], 0
	v_mov_b64_e32 v[90:91], 0
	v_mov_b64_e32 v[36:37], 0
	v_mov_b64_e32 v[38:39], 0
	v_mov_b64_e32 v[44:45], 0
	v_mov_b64_e32 v[46:47], 0
	v_mov_b64_e32 v[52:53], 0
	v_mov_b64_e32 v[54:55], 0
	v_mov_b64_e32 v[60:61], 0
	v_mov_b64_e32 v[62:63], 0
	v_mov_b64_e32 v[68:69], 0
	v_mov_b64_e32 v[70:71], 0
	v_mov_b64_e32 v[76:77], 0
	v_mov_b64_e32 v[78:79], 0
	v_mov_b64_e32 v[84:85], 0
	v_mov_b64_e32 v[86:87], 0
	v_mov_b64_e32 v[92:93], 0
	v_mov_b64_e32 v[94:95], 0
	v_mov_b64_e32 v[96:97], 0
	v_mov_b64_e32 v[98:99], 0
	v_mov_b64_e32 v[104:105], 0
	v_mov_b64_e32 v[106:107], 0
	v_mov_b64_e32 v[112:113], 0
	v_mov_b64_e32 v[114:115], 0
	v_mov_b64_e32 v[120:121], 0
	v_mov_b64_e32 v[122:123], 0
	v_mov_b64_e32 v[128:129], 0
	v_mov_b64_e32 v[130:131], 0
	v_mov_b64_e32 v[136:137], 0
	v_mov_b64_e32 v[138:139], 0
	v_mov_b64_e32 v[144:145], 0
	v_mov_b64_e32 v[146:147], 0
	v_mov_b64_e32 v[152:153], 0
	v_mov_b64_e32 v[154:155], 0
	v_mov_b64_e32 v[100:101], 0
	v_mov_b64_e32 v[102:103], 0
	v_mov_b64_e32 v[108:109], 0
	v_mov_b64_e32 v[110:111], 0
	v_mov_b64_e32 v[116:117], 0
	v_mov_b64_e32 v[118:119], 0
	v_mov_b64_e32 v[124:125], 0
	v_mov_b64_e32 v[126:127], 0
	v_mov_b64_e32 v[132:133], 0
	v_mov_b64_e32 v[134:135], 0
	v_mov_b64_e32 v[140:141], 0
	v_mov_b64_e32 v[142:143], 0
	v_mov_b64_e32 v[148:149], 0
	v_mov_b64_e32 v[150:151], 0
	v_mov_b64_e32 v[156:157], 0
	v_mov_b64_e32 v[158:159], 0

.LBB0_583:
	s_waitcnt vmcnt(0)
	v_lshl_add_u32 v0, s26, 6, v64
	s_mov_b32 s2, 0x100000
	v_cmp_gt_i32_e32 vcc, s2, v0
	s_and_saveexec_b64 s[2:3], vcc
	s_cbranch_execz .LBB0_586
	s_load_dwordx2 s[12:13], s[0:1], 0x8
	s_lshl_b32 s4, s14, 9
	v_ashrrev_i32_e32 v1, 31, v0
	s_waitcnt lgkmcnt(0)
	v_lshl_add_u64 v[2:3], v[0:1], 3, s[6:7]
	s_mov_b64 s[10:11], 0x1ff00000
	s_ashr_i32 s5, s4, 31
	v_lshl_add_u64 v[2:3], v[2:3], 0, s[10:11]
	s_lshl_b64 s[10:11], s[4:5], 3
	v_lshl_add_u64 v[4:5], v[0:1], 4, s[12:13]
	s_lshl_b64 s[12:13], s[4:5], 4
	s_lshl_b32 s15, s26, 6
.LBB0_585:
	global_load_dwordx4 v[6:9], v[4:5], off
	v_lshl_add_u64 v[48:49], v[4:5], 0, s[12:13]
	s_mov_b32 s14, 1
	s_add_i32 s5, s15, s4
	s_cmp_lt_i32 s5, 0x100000
	s_cbranch_scc0 .Lp_ld_done
	global_load_dwordx4 v[10:13], v[48:49], off
	v_lshl_add_u64 v[48:49], v[48:49], 0, s[12:13]
	s_mov_b32 s14, 2
	s_add_i32 s5, s5, s4
	s_cmp_lt_i32 s5, 0x100000
	s_cbranch_scc0 .Lp_ld_done
	global_load_dwordx4 v[14:17], v[48:49], off
	v_lshl_add_u64 v[48:49], v[48:49], 0, s[12:13]
	s_mov_b32 s14, 3
	s_add_i32 s5, s5, s4
	s_cmp_lt_i32 s5, 0x100000
	s_cbranch_scc0 .Lp_ld_done
	global_load_dwordx4 v[18:21], v[48:49], off
	v_lshl_add_u64 v[48:49], v[48:49], 0, s[12:13]
	s_mov_b32 s14, 4
	s_add_i32 s5, s5, s4
.Lp_ld_done:
	s_waitcnt vmcnt(0)
	v_cvt_pk_bf16_f32 v22, v6, v7
	v_cvt_pk_bf16_f32 v23, v8, v9
	global_store_dwordx2 v[2:3], v[22:23], off
	v_lshl_add_u64 v[2:3], v[2:3], 0, s[10:11]
	s_cmp_lt_u32 s14, 2
	s_cbranch_scc1 .Lp_st_done
	v_cvt_pk_bf16_f32 v24, v10, v11
	v_cvt_pk_bf16_f32 v25, v12, v13
	global_store_dwordx2 v[2:3], v[24:25], off
	v_lshl_add_u64 v[2:3], v[2:3], 0, s[10:11]
	s_cmp_lt_u32 s14, 3
	s_cbranch_scc1 .Lp_st_done
	v_cvt_pk_bf16_f32 v26, v14, v15
	v_cvt_pk_bf16_f32 v27, v16, v17
	global_store_dwordx2 v[2:3], v[26:27], off
	v_lshl_add_u64 v[2:3], v[2:3], 0, s[10:11]
	s_cmp_lt_u32 s14, 4
	s_cbranch_scc1 .Lp_st_done
	v_cvt_pk_bf16_f32 v28, v18, v19
	v_cvt_pk_bf16_f32 v29, v20, v21
	global_store_dwordx2 v[2:3], v[28:29], off
	v_lshl_add_u64 v[2:3], v[2:3], 0, s[10:11]
	s_mov_b32 s15, s5
	v_mov_b64_e32 v[4:5], v[48:49]
	s_cmp_lt_i32 s15, 0x100000
	s_cbranch_scc1 .LBB0_585
.Lp_st_done:
.LBB0_586:
	s_or_b64 exec, exec, s[2:3]
	s_cmpk_gt_i32 s26, 0xaff
	s_movk_i32 s23, 0xb00
	s_cselect_b64 s[2:3], -1, 0
